# mixa attention softmax: running max over raw scores then one scale (drops 28 v_mul per key block; identical values)
# speedup vs baseline: 1.0058x; 1.0013x over previous
.LBB0_348:
	s_add_i32 s20, s21, 1
	s_bitcmp1_b32 s20, 0
	s_cselect_b32 s16, 0x4800, 0
	v_add_u32_e32 v66, s16, v69
	s_min_i32 s16, s21, 21
	s_lshl_b32 s22, s16, 6
	s_waitcnt vmcnt(3)
	ds_write_b128 v66, v[50:53]
	s_waitcnt vmcnt(2)
	ds_write_b128 v66, v[54:57] offset:9216
	s_waitcnt vmcnt(1)
	ds_write_b128 v66, v[58:61] offset:4608
	s_waitcnt vmcnt(0)
	ds_write_b128 v66, v[62:65] offset:13824
	v_add_lshl_u32 v66, s22, v152, 9
	s_lshl_b32 s16, s16, 7
	v_lshl_add_u64 v[58:59], v[116:117], 0, v[66:67]
	v_lshl_add_u64 v[62:63], v[118:119], 0, s[16:17]
	s_bitcmp1_b32 s21, 0
	global_load_dwordx4 v[50:53], v[58:59], off
	global_load_dwordx4 v[54:57], v[62:63], off offset:256
	v_add_co_u32_e32 v58, vcc, s19, v58
	s_cselect_b32 s16, 0x4800, 0
	s_nop 0
	v_addc_co_u32_e32 v59, vcc, 0, v59, vcc
	s_add_i32 s16, s16, 32
	v_add_co_u32_e32 v62, vcc, s96, v62
	v_add_u32_e32 v97, s16, v151
	s_nop 0
	v_addc_co_u32_e32 v63, vcc, 0, v63, vcc
	v_lshl_add_u32 v66, v68, 1, v97
	global_load_dwordx4 v[58:61], v[58:59], off
	s_cmp_lg_u32 s20, 24
	global_load_dwordx4 v[62:65], v[62:63], off offset:256
	ds_read_b128 v[158:161], v66
	ds_read_b128 v[162:165], v66 offset:64
	s_waitcnt lgkmcnt(1)
	v_mfma_f32_16x16x32_bf16 v[166:169], v[158:161], v[34:37], 0
	s_mov_b32 s21, s20
	v_mfma_f32_16x16x32_bf16 v[158:161], v[158:161], v[46:49], 0
	s_waitcnt lgkmcnt(0)
	v_mfma_f32_16x16x32_bf16 v[166:169], v[162:165], v[42:45], v[166:169]
	v_mfma_f32_16x16x32_bf16 v[158:161], v[162:165], v[38:41], v[158:161]
	ds_read_b128 v[162:165], v66 offset:2304
	ds_read_b128 v[170:173], v66 offset:2368
	s_nop 4
	s_waitcnt lgkmcnt(1)
	v_mfma_f32_16x16x32_bf16 v[174:177], v[162:165], v[34:37], 0
	v_mfma_f32_16x16x32_bf16 v[162:165], v[162:165], v[46:49], 0
	s_waitcnt lgkmcnt(0)
	v_mfma_f32_16x16x32_bf16 v[174:177], v[170:173], v[42:45], v[174:177]
	v_mfma_f32_16x16x32_bf16 v[162:165], v[170:173], v[38:41], v[162:165]
	ds_read_b128 v[170:173], v66 offset:4608
	ds_read_b128 v[188:191], v66 offset:4672
	s_waitcnt lgkmcnt(1)
	v_mfma_f32_16x16x32_bf16 v[192:195], v[170:173], v[34:37], 0
	v_mfma_f32_16x16x32_bf16 v[170:173], v[170:173], v[46:49], 0
	s_waitcnt lgkmcnt(0)
	v_mfma_f32_16x16x32_bf16 v[192:195], v[188:191], v[42:45], v[192:195]
	v_mfma_f32_16x16x32_bf16 v[170:173], v[188:191], v[38:41], v[170:173]
	ds_read_b128 v[188:191], v66 offset:6912
	ds_read_b128 v[196:199], v66 offset:6976
	v_max3_f32 v66, v166, s97, v167
	s_waitcnt lgkmcnt(1)
	v_mfma_f32_16x16x32_bf16 v[200:203], v[188:191], v[34:37], 0
	v_max3_f32 v66, v66, v168, v169
	s_waitcnt lgkmcnt(0)
	v_mfma_f32_16x16x32_bf16 v[200:203], v[196:199], v[42:45], v[200:203]
	v_max3_f32 v66, v66, v174, v175
	v_max3_f32 v66, v66, v176, v177
	v_max3_f32 v66, v66, v192, v193
	v_max3_f32 v66, v66, v194, v195
	v_max3_f32 v66, v66, v200, v201
	v_max3_f32 v66, v66, v202, v203
	ds_bpermute_b32 v91, v89, v66
	v_mfma_f32_16x16x32_bf16 v[188:191], v[188:191], v[46:49], 0
	s_waitcnt lgkmcnt(0)
	v_max_f32_e32 v91, v91, v91
	v_max_f32_e32 v66, v66, v91
	ds_bpermute_b32 v91, v87, v66
	v_mfma_f32_16x16x32_bf16 v[188:191], v[196:199], v[38:41], v[188:191]
	s_waitcnt lgkmcnt(0)
	v_max_f32_e32 v66, v66, v91
	v_mul_f32_e32 v66, 0x3fb8aa3b, v66
	v_max_f32_e32 v66, v95, v66
	v_sub_f32_e32 v91, v95, v66
	v_exp_f32_e32 v180, v91
	v_fma_f32 v91, v166, s81, -v66
	v_exp_f32_e32 v166, v91
	v_fma_f32 v91, v167, s81, -v66
	v_exp_f32_e32 v184, v91
	v_fma_f32 v91, v168, s81, -v66
	v_exp_f32_e32 v168, v91
	v_fma_f32 v91, v169, s81, -v66
	v_exp_f32_e32 v196, v91
	v_fma_f32 v91, v174, s81, -v66
	v_exp_f32_e32 v174, v91
	v_fma_f32 v91, v175, s81, -v66
	v_exp_f32_e32 v198, v91
	v_fma_f32 v91, v176, s81, -v66
	v_exp_f32_e32 v176, v91
	v_fma_f32 v91, v177, s81, -v66
	v_exp_f32_e32 v204, v91
	v_fma_f32 v91, v192, s81, -v66
	v_exp_f32_e32 v192, v91
	v_fma_f32 v91, v193, s81, -v66
	v_exp_f32_e32 v206, v91
	v_fma_f32 v91, v194, s81, -v66
	v_exp_f32_e32 v194, v91
	v_fma_f32 v91, v195, s81, -v66
	v_exp_f32_e32 v208, v91
	v_fma_f32 v91, v200, s81, -v66
	v_exp_f32_e32 v200, v91
	v_fma_f32 v91, v201, s81, -v66
	v_exp_f32_e32 v210, v91
	v_fma_f32 v91, v202, s81, -v66
	v_exp_f32_e32 v202, v91
	v_fma_f32 v91, v203, s81, -v66
	v_exp_f32_e32 v212, v91
	v_max3_f32 v91, v158, s97, v159
	v_max3_f32 v91, v91, v160, v161
	v_max3_f32 v91, v91, v162, v163
	v_max3_f32 v91, v91, v164, v165
	v_max3_f32 v91, v91, v170, v171
	v_max3_f32 v91, v91, v172, v173
	v_max3_f32 v91, v91, v188, v189
	v_max3_f32 v91, v91, v190, v191
	ds_bpermute_b32 v95, v89, v91
	s_waitcnt lgkmcnt(0)
	v_max_f32_e32 v95, v95, v95
	v_max_f32_e32 v91, v91, v95
	ds_bpermute_b32 v95, v87, v91
	s_waitcnt lgkmcnt(0)
	v_max_f32_e32 v91, v91, v95
	v_mul_f32_e32 v91, 0x3fb8aa3b, v91
	v_max_f32_e32 v91, v93, v91
	v_sub_f32_e32 v93, v93, v91
	v_exp_f32_e32 v181, v93
	v_fma_f32 v93, v158, s81, -v91
	v_exp_f32_e32 v167, v93
	v_fma_f32 v93, v159, s81, -v91
	v_exp_f32_e32 v185, v93
	v_fma_f32 v93, v160, s81, -v91
	v_exp_f32_e32 v169, v93
	v_fma_f32 v93, v161, s81, -v91
	v_exp_f32_e32 v197, v93
	v_fma_f32 v93, v162, s81, -v91
	v_exp_f32_e32 v175, v93
	v_fma_f32 v93, v163, s81, -v91
	v_exp_f32_e32 v199, v93
	v_fma_f32 v93, v164, s81, -v91
	v_exp_f32_e32 v177, v93
	v_fma_f32 v93, v165, s81, -v91
	v_exp_f32_e32 v205, v93
	v_fma_f32 v93, v170, s81, -v91
	v_exp_f32_e32 v193, v93
	v_fma_f32 v93, v171, s81, -v91
	v_exp_f32_e32 v207, v93
	v_fma_f32 v93, v172, s81, -v91
	v_exp_f32_e32 v195, v93
	v_fma_f32 v93, v173, s81, -v91
	v_pk_add_f32 v[162:163], v[166:167], 0 op_sel_hi:[1,0]
	v_exp_f32_e32 v209, v93
	v_fma_f32 v93, v188, s81, -v91
	v_pk_add_f32 v[162:163], v[184:185], v[162:163]
	v_exp_f32_e32 v201, v93
	v_fma_f32 v93, v189, s81, -v91
	v_pk_add_f32 v[162:163], v[168:169], v[162:163]
	v_exp_f32_e32 v211, v93
	v_fma_f32 v93, v190, s81, -v91
	v_pk_add_f32 v[162:163], v[196:197], v[162:163]
	v_exp_f32_e32 v203, v93
	v_fma_f32 v93, v191, s81, -v91
	v_pk_add_f32 v[162:163], v[174:175], v[162:163]
	v_exp_f32_e32 v213, v93
	v_add_u32_e32 v93, v97, v68
	v_cvt_pk_bf16_f32 v158, v166, v184
	v_pk_add_f32 v[214:215], v[198:199], v[162:163]
	v_mov_b32_e32 v166, v181
	v_add_u32_e32 v95, 0x2000, v93
	v_cvt_pk_bf16_f32 v159, v168, v196
	v_cvt_pk_bf16_f32 v160, v174, v198
	v_cvt_pk_bf16_f32 v161, v176, v204
	v_pk_add_f32 v[170:171], v[176:177], v[214:215]
	v_pk_mul_f32 v[8:9], v[8:9], v[166:167] op_sel_hi:[1,0]
	v_pk_mul_f32 v[6:7], v[6:7], v[166:167] op_sel_hi:[1,0]
	v_pk_mul_f32 v[4:5], v[4:5], v[166:167] op_sel_hi:[1,0]
	v_pk_mul_f32 v[2:3], v[2:3], v[166:167] op_sel_hi:[1,0]
	v_pk_mul_f32 v[12:13], v[12:13], v[166:167] op_sel_hi:[1,0]
	v_pk_mul_f32 v[10:11], v[10:11], v[166:167] op_sel_hi:[1,0]
	v_pk_mul_f32 v[16:17], v[16:17], v[166:167] op_sel_hi:[1,0]
	v_pk_mul_f32 v[14:15], v[14:15], v[166:167] op_sel_hi:[1,0]
	v_cvt_pk_bf16_f32 v166, v167, v185
	v_cvt_pk_bf16_f32 v167, v169, v197
	v_cvt_pk_bf16_f32 v168, v175, v199
	v_cvt_pk_bf16_f32 v169, v177, v205
	ds_read2_b64 v[174:177], v95 offset0:128 offset1:132
	v_pk_mul_f32 v[28:29], v[28:29], v[180:181] op_sel_hi:[1,0]
	v_pk_mul_f32 v[26:27], v[26:27], v[180:181] op_sel_hi:[1,0]
	v_pk_add_f32 v[170:171], v[204:205], v[170:171]
	s_waitcnt lgkmcnt(0)
	v_mfma_f32_16x16x32_bf16 v[6:9], v[174:177], v[166:169], v[6:9]
	v_add_f32_e64 v170, v192, v170
	v_add_f32_e64 v171, v193, v171
	v_cvt_pk_bf16_f32 v162, v192, v206
	v_pk_add_f32 v[170:171], v[206:207], v[170:171]
	v_mfma_f32_16x16x32_bf16 v[26:29], v[174:177], v[158:161], v[26:29]
	ds_read2_b64 v[174:177], v95 offset0:136 offset1:140
	v_pk_add_f32 v[170:171], v[194:195], v[170:171]
	v_cvt_pk_bf16_f32 v163, v194, v208
	v_pk_add_f32 v[170:171], v[208:209], v[170:171]
	v_cvt_pk_bf16_f32 v164, v200, v210
	v_pk_add_f32 v[170:171], v[200:201], v[170:171]
	v_cvt_pk_bf16_f32 v165, v202, v212
	v_pk_add_f32 v[170:171], v[210:211], v[170:171]
	v_cvt_pk_bf16_f32 v172, v201, v211
	v_pk_add_f32 v[170:171], v[202:203], v[170:171]
	v_cvt_pk_bf16_f32 v173, v203, v213
	v_pk_add_f32 v[170:171], v[212:213], v[170:171]
	v_add_u32_e32 v95, 0x2800, v93
	v_pk_fma_f32 v[112:113], v[112:113], v[180:181], v[170:171]
	v_cvt_pk_bf16_f32 v170, v193, v207
	v_cvt_pk_bf16_f32 v171, v195, v209
	s_waitcnt lgkmcnt(0)
	v_mfma_f32_16x16x32_bf16 v[26:29], v[174:177], v[162:165], v[26:29]
	v_mul_f32_e64 v20, v20, v180
	v_mul_f32_e64 v21, v21, v180
	v_pk_mul_f32 v[18:19], v[18:19], v[180:181] op_sel_hi:[1,0]
	v_pk_mul_f32 v[24:25], v[24:25], v[180:181] op_sel_hi:[1,0]
	v_mfma_f32_16x16x32_bf16 v[6:9], v[174:177], v[170:173], v[6:9]
	ds_read2_b64 v[174:177], v95 offset0:160 offset1:164
	v_pk_mul_f32 v[22:23], v[22:23], v[180:181] op_sel_hi:[1,0]
	v_pk_mul_f32 v[32:33], v[32:33], v[180:181] op_sel_hi:[1,0]
	s_waitcnt lgkmcnt(0)
	v_mfma_f32_16x16x32_bf16 v[18:21], v[174:177], v[158:161], v[18:21]
	v_mul_f32_e64 v30, v30, v180
	v_mul_f32_e64 v31, v31, v180
	v_mfma_f32_16x16x32_bf16 v[2:5], v[174:177], v[166:169], v[2:5]
	ds_read2_b64 v[174:177], v95 offset0:168 offset1:172
	v_add_u32_e32 v95, 0x3000, v93
	v_add_u32_e32 v93, 0x3800, v93
	s_waitcnt lgkmcnt(0)
	v_mfma_f32_16x16x32_bf16 v[18:21], v[174:177], v[162:165], v[18:21]
	v_mfma_f32_16x16x32_bf16 v[2:5], v[174:177], v[170:173], v[2:5]
	ds_read2_b64 v[174:177], v95 offset0:192 offset1:196
	s_waitcnt lgkmcnt(0)
	v_mfma_f32_16x16x32_bf16 v[22:25], v[174:177], v[158:161], v[22:25]
	v_mfma_f32_16x16x32_bf16 v[10:13], v[174:177], v[166:169], v[10:13]
	ds_read2_b64 v[174:177], v95 offset0:200 offset1:204
	v_mov_b32_e32 v95, v66
	s_waitcnt lgkmcnt(0)
	v_mfma_f32_16x16x32_bf16 v[22:25], v[174:177], v[162:165], v[22:25]
	v_mfma_f32_16x16x32_bf16 v[10:13], v[174:177], v[170:173], v[10:13]
	ds_read2_b64 v[174:177], v93 offset0:224 offset1:228
	s_waitcnt lgkmcnt(0)
	v_mfma_f32_16x16x32_bf16 v[30:33], v[174:177], v[158:161], v[30:33]
	ds_read2_b64 v[158:161], v93 offset0:232 offset1:236
	v_mov_b32_e32 v93, v91
	s_waitcnt lgkmcnt(0)
	v_mfma_f32_16x16x32_bf16 v[14:17], v[174:177], v[166:169], v[14:17]
	s_barrier
	v_mfma_f32_16x16x32_bf16 v[30:33], v[158:161], v[162:165], v[30:33]
	v_mfma_f32_16x16x32_bf16 v[14:17], v[158:161], v[170:173], v[14:17]
	s_cbranch_scc1 .LBB0_348
	ds_bpermute_b32 v37, v89, v112
	v_or_b32_e32 v36, v114, v140
	s_lshl_b32 s16, s9, 1
	v_lshl_add_u64 v[34:35], v[84:85], 0, s[16:17]
	s_waitcnt lgkmcnt(0)
	v_add_f32_e32 v37, v112, v37
	ds_bpermute_b32 v38, v87, v37
	s_waitcnt lgkmcnt(0)
	v_add_f32_e32 v37, v37, v38
	v_div_scale_f32 v38, s[20:21], v37, v37, 1.0
	v_rcp_f32_e32 v39, v38
	s_nop 0
	v_fma_f32 v40, -v38, v39, 1.0
	v_fmac_f32_e32 v39, v40, v39
	v_div_scale_f32 v40, vcc, 1.0, v37, 1.0
	v_mul_f32_e32 v41, v40, v39
	v_fma_f32 v42, -v38, v41, v40
	v_fmac_f32_e32 v41, v42, v39
	v_fma_f32 v38, -v38, v41, v40
	v_div_fmas_f32 v38, v38, v39, v41
	v_div_fixup_f32 v38, v38, v37, 1.0
	v_ashrrev_i32_e32 v37, 31, v36
	v_lshlrev_b64 v[40:41], 11, v[36:37]
	v_pk_mul_f32 v[18:19], v[18:19], v[38:39] op_sel_hi:[1,0]
	v_pk_mul_f32 v[20:21], v[20:21], v[38:39] op_sel_hi:[1,0]
	v_lshl_add_u64 v[40:41], v[34:35], 0, v[40:41]
	v_cvt_pk_bf16_f32 v18, v18, v19
	v_cvt_pk_bf16_f32 v19, v20, v21
	global_store_dwordx2 v[40:41], v[18:19], off offset:32
	v_pk_mul_f32 v[18:19], v[22:23], v[38:39] op_sel_hi:[1,0]
	v_pk_mul_f32 v[20:21], v[24:25], v[38:39] op_sel_hi:[1,0]
	v_cvt_pk_bf16_f32 v18, v18, v19
	v_cvt_pk_bf16_f32 v19, v20, v21
	global_store_dwordx2 v[40:41], v[18:19], off offset:64
	v_pk_mul_f32 v[18:19], v[30:31], v[38:39] op_sel_hi:[1,0]
	v_pk_mul_f32 v[20:21], v[32:33], v[38:39] op_sel_hi:[1,0]
	v_cvt_pk_bf16_f32 v18, v18, v19
	v_cvt_pk_bf16_f32 v19, v20, v21
	global_store_dwordx2 v[40:41], v[18:19], off offset:96
	ds_bpermute_b32 v18, v89, v113
	v_pk_mul_f32 v[26:27], v[26:27], v[38:39] op_sel_hi:[1,0]
	v_pk_mul_f32 v[28:29], v[28:29], v[38:39] op_sel_hi:[1,0]
	v_cvt_pk_bf16_f32 v26, v26, v27
	v_cvt_pk_bf16_f32 v27, v28, v29
	s_waitcnt lgkmcnt(0)
	v_add_f32_e32 v18, v113, v18
	ds_bpermute_b32 v19, v87, v18
	global_store_dwordx2 v[40:41], v[26:27], off
	s_waitcnt lgkmcnt(0)
	v_add_f32_e32 v18, v18, v19
	v_div_scale_f32 v19, s[20:21], v18, v18, 1.0
	v_rcp_f32_e32 v20, v19
	s_nop 0
	v_fma_f32 v21, -v19, v20, 1.0
	v_fmac_f32_e32 v20, v21, v20
	v_div_scale_f32 v21, vcc, 1.0, v18, 1.0
	v_mul_f32_e32 v22, v21, v20
	v_fma_f32 v23, -v19, v22, v21
	v_fmac_f32_e32 v22, v23, v20
	v_fma_f32 v19, -v19, v22, v21
	v_div_fmas_f32 v19, v19, v20, v22
	v_or_b32_e32 v20, 16, v36
	v_div_fixup_f32 v18, v19, v18, 1.0
	v_ashrrev_i32_e32 v21, 31, v20
	v_lshlrev_b64 v[20:21], 11, v[20:21]
	v_pk_mul_f32 v[2:3], v[2:3], v[18:19] op_sel_hi:[1,0]
	v_pk_mul_f32 v[4:5], v[4:5], v[18:19] op_sel_hi:[1,0]
	v_lshl_add_u64 v[20:21], v[34:35], 0, v[20:21]
	v_cvt_pk_bf16_f32 v2, v2, v3
	v_cvt_pk_bf16_f32 v3, v4, v5
	global_store_dwordx2 v[20:21], v[2:3], off offset:32
	v_pk_mul_f32 v[2:3], v[10:11], v[18:19] op_sel_hi:[1,0]
	v_pk_mul_f32 v[4:5], v[12:13], v[18:19] op_sel_hi:[1,0]
	v_cvt_pk_bf16_f32 v2, v2, v3
	v_cvt_pk_bf16_f32 v3, v4, v5
	v_pk_mul_f32 v[6:7], v[6:7], v[18:19] op_sel_hi:[1,0]
	v_pk_mul_f32 v[8:9], v[8:9], v[18:19] op_sel_hi:[1,0]
	global_store_dwordx2 v[20:21], v[2:3], off offset:64
	v_pk_mul_f32 v[2:3], v[14:15], v[18:19] op_sel_hi:[1,0]
	v_pk_mul_f32 v[4:5], v[16:17], v[18:19] op_sel_hi:[1,0]
	v_cvt_pk_bf16_f32 v6, v6, v7
	v_cvt_pk_bf16_f32 v7, v8, v9
	v_cvt_pk_bf16_f32 v2, v2, v3
	v_cvt_pk_bf16_f32 v3, v4, v5
	global_store_dwordx2 v[20:21], v[6:7], off
	global_store_dwordx2 v[20:21], v[2:3], off offset:96
	s_branch .LBB0_313

.LBB0_1088:
	s_add_i32 s11, s12, 1
	s_bitcmp1_b32 s11, 0
	s_cselect_b32 s13, 0x4800, 0
	v_add_u32_e32 v66, s13, v69
	s_min_i32 s13, s12, 21
	s_lshl_b32 s14, s13, 6
	s_waitcnt vmcnt(3)
	ds_write_b128 v66, v[50:53]
	s_waitcnt vmcnt(2)
	ds_write_b128 v66, v[54:57] offset:9216
	s_waitcnt vmcnt(1)
	ds_write_b128 v66, v[58:61] offset:4608
	s_waitcnt vmcnt(0)
	ds_write_b128 v66, v[62:65] offset:13824
	v_add_lshl_u32 v66, s14, v153, 9
	s_lshl_b32 s96, s13, 7
	v_lshl_add_u64 v[58:59], v[116:117], 0, v[66:67]
	v_lshl_add_u64 v[62:63], v[118:119], 0, s[96:97]
	s_bitcmp1_b32 s12, 0
	global_load_dwordx4 v[50:53], v[58:59], off
	global_load_dwordx4 v[54:57], v[62:63], off offset:256
	v_add_co_u32_e32 v58, vcc, s9, v58
	s_cselect_b32 s12, 0x4800, 0
	s_nop 0
	v_addc_co_u32_e32 v59, vcc, 0, v59, vcc
	s_add_i32 s12, s12, 32
	v_add_co_u32_e32 v62, vcc, s28, v62
	v_add_u32_e32 v97, s12, v152
	s_nop 0
	v_addc_co_u32_e32 v63, vcc, 0, v63, vcc
	v_lshl_add_u32 v66, v68, 1, v97
	global_load_dwordx4 v[58:61], v[58:59], off
	s_cmp_lg_u32 s11, 24
	global_load_dwordx4 v[62:65], v[62:63], off offset:256
	ds_read_b128 v[158:161], v66
	ds_read_b128 v[162:165], v66 offset:64
	s_waitcnt lgkmcnt(1)
	v_mfma_f32_16x16x32_bf16 v[166:169], v[158:161], v[34:37], 0
	s_mov_b32 s12, s11
	v_mfma_f32_16x16x32_bf16 v[158:161], v[158:161], v[46:49], 0
	s_waitcnt lgkmcnt(0)
	v_mfma_f32_16x16x32_bf16 v[166:169], v[162:165], v[42:45], v[166:169]
	v_mfma_f32_16x16x32_bf16 v[158:161], v[162:165], v[38:41], v[158:161]
	ds_read_b128 v[162:165], v66 offset:2304
	ds_read_b128 v[170:173], v66 offset:2368
	s_nop 4
	s_waitcnt lgkmcnt(1)
	v_mfma_f32_16x16x32_bf16 v[174:177], v[162:165], v[34:37], 0
	v_mfma_f32_16x16x32_bf16 v[162:165], v[162:165], v[46:49], 0
	s_waitcnt lgkmcnt(0)
	v_mfma_f32_16x16x32_bf16 v[174:177], v[170:173], v[42:45], v[174:177]
	v_mfma_f32_16x16x32_bf16 v[162:165], v[170:173], v[38:41], v[162:165]
	ds_read_b128 v[170:173], v66 offset:4608
	ds_read_b128 v[178:181], v66 offset:4672
	s_waitcnt lgkmcnt(1)
	v_mfma_f32_16x16x32_bf16 v[182:185], v[170:173], v[34:37], 0
	v_mfma_f32_16x16x32_bf16 v[170:173], v[170:173], v[46:49], 0
	s_waitcnt lgkmcnt(0)
	v_mfma_f32_16x16x32_bf16 v[182:185], v[178:181], v[42:45], v[182:185]
	v_mfma_f32_16x16x32_bf16 v[170:173], v[178:181], v[38:41], v[170:173]
	ds_read_b128 v[178:181], v66 offset:6912
	ds_read_b128 v[186:189], v66 offset:6976
	v_max3_f32 v66, v166, s29, v167
	s_waitcnt lgkmcnt(1)
	v_mfma_f32_16x16x32_bf16 v[190:193], v[178:181], v[34:37], 0
	v_max3_f32 v66, v66, v168, v169
	s_waitcnt lgkmcnt(0)
	v_mfma_f32_16x16x32_bf16 v[190:193], v[186:189], v[42:45], v[190:193]
	v_max3_f32 v66, v66, v174, v175
	v_max3_f32 v66, v66, v176, v177
	v_max3_f32 v66, v66, v182, v183
	v_max3_f32 v66, v66, v184, v185
	v_max3_f32 v66, v66, v190, v191
	v_max3_f32 v66, v66, v192, v193
	ds_bpermute_b32 v91, v89, v66
	v_mfma_f32_16x16x32_bf16 v[178:181], v[178:181], v[46:49], 0
	s_waitcnt lgkmcnt(0)
	v_max_f32_e32 v91, v91, v91
	v_max_f32_e32 v66, v66, v91
	ds_bpermute_b32 v91, v87, v66
	v_mfma_f32_16x16x32_bf16 v[178:181], v[186:189], v[38:41], v[178:181]
	s_waitcnt lgkmcnt(0)
	v_max_f32_e32 v66, v66, v91
	v_mul_f32_e32 v66, 0x3fb8aa3b, v66
	v_max_f32_e32 v66, v95, v66
	v_sub_f32_e32 v91, v95, v66
	v_exp_f32_e32 v186, v91
	v_fma_f32 v91, v166, s27, -v66
	v_exp_f32_e32 v166, v91
	v_fma_f32 v91, v167, s27, -v66
	v_exp_f32_e32 v188, v91
	v_fma_f32 v91, v168, s27, -v66
	v_exp_f32_e32 v168, v91
	v_fma_f32 v91, v169, s27, -v66
	v_exp_f32_e32 v194, v91
	v_fma_f32 v91, v174, s27, -v66
	v_exp_f32_e32 v174, v91
	v_fma_f32 v91, v175, s27, -v66
	v_exp_f32_e32 v196, v91
	v_fma_f32 v91, v176, s27, -v66
	v_exp_f32_e32 v176, v91
	v_fma_f32 v91, v177, s27, -v66
	v_exp_f32_e32 v198, v91
	v_fma_f32 v91, v182, s27, -v66
	v_exp_f32_e32 v182, v91
	v_fma_f32 v91, v183, s27, -v66
	v_exp_f32_e32 v200, v91
	v_fma_f32 v91, v184, s27, -v66
	v_exp_f32_e32 v184, v91
	v_fma_f32 v91, v185, s27, -v66
	v_exp_f32_e32 v202, v91
	v_fma_f32 v91, v190, s27, -v66
	v_exp_f32_e32 v190, v91
	v_fma_f32 v91, v191, s27, -v66
	v_exp_f32_e32 v204, v91
	v_fma_f32 v91, v192, s27, -v66
	v_exp_f32_e32 v192, v91
	v_fma_f32 v91, v193, s27, -v66
	v_exp_f32_e32 v206, v91
	v_max3_f32 v91, v158, s29, v159
	v_max3_f32 v91, v91, v160, v161
	v_max3_f32 v91, v91, v162, v163
	v_max3_f32 v91, v91, v164, v165
	v_max3_f32 v91, v91, v170, v171
	v_max3_f32 v91, v91, v172, v173
	v_max3_f32 v91, v91, v178, v179
	v_max3_f32 v91, v91, v180, v181
	ds_bpermute_b32 v95, v89, v91
	s_waitcnt lgkmcnt(0)
	v_max_f32_e32 v95, v95, v95
	v_max_f32_e32 v91, v91, v95
	ds_bpermute_b32 v95, v87, v91
	s_waitcnt lgkmcnt(0)
	v_max_f32_e32 v91, v91, v95
	v_mul_f32_e32 v91, 0x3fb8aa3b, v91
	v_max_f32_e32 v91, v93, v91
	v_sub_f32_e32 v93, v93, v91
	v_exp_f32_e32 v187, v93
	v_fma_f32 v93, v158, s27, -v91
	v_exp_f32_e32 v167, v93
	v_fma_f32 v93, v159, s27, -v91
	v_exp_f32_e32 v189, v93
	v_fma_f32 v93, v160, s27, -v91
	v_exp_f32_e32 v169, v93
	v_fma_f32 v93, v161, s27, -v91
	v_exp_f32_e32 v195, v93
	v_fma_f32 v93, v162, s27, -v91
	v_exp_f32_e32 v175, v93
	v_fma_f32 v93, v163, s27, -v91
	v_exp_f32_e32 v197, v93
	v_fma_f32 v93, v164, s27, -v91
	v_exp_f32_e32 v177, v93
	v_fma_f32 v93, v165, s27, -v91
	v_exp_f32_e32 v199, v93
	v_fma_f32 v93, v170, s27, -v91
	v_exp_f32_e32 v183, v93
	v_fma_f32 v93, v171, s27, -v91
	v_exp_f32_e32 v201, v93
	v_fma_f32 v93, v172, s27, -v91
	v_exp_f32_e32 v185, v93
	v_fma_f32 v93, v173, s27, -v91
	v_pk_add_f32 v[162:163], v[166:167], 0 op_sel_hi:[1,0]
	v_exp_f32_e32 v203, v93
	v_fma_f32 v93, v178, s27, -v91
	v_pk_add_f32 v[162:163], v[188:189], v[162:163]
	v_exp_f32_e32 v191, v93
	v_fma_f32 v93, v179, s27, -v91
	v_pk_add_f32 v[162:163], v[168:169], v[162:163]
	v_exp_f32_e32 v205, v93
	v_fma_f32 v93, v180, s27, -v91
	v_pk_add_f32 v[162:163], v[194:195], v[162:163]
	v_exp_f32_e32 v193, v93
	v_fma_f32 v93, v181, s27, -v91
	v_pk_add_f32 v[162:163], v[174:175], v[162:163]
	v_exp_f32_e32 v207, v93
	v_add_u32_e32 v93, v97, v68
	v_cvt_pk_bf16_f32 v158, v166, v188
	v_pk_add_f32 v[208:209], v[196:197], v[162:163]
	v_mov_b32_e32 v166, v187
	v_add_u32_e32 v95, 0x2000, v93
	v_cvt_pk_bf16_f32 v159, v168, v194
	v_cvt_pk_bf16_f32 v160, v174, v196
	v_cvt_pk_bf16_f32 v161, v176, v198
	v_pk_add_f32 v[170:171], v[176:177], v[208:209]
	v_pk_mul_f32 v[8:9], v[8:9], v[166:167] op_sel_hi:[1,0]
	v_pk_mul_f32 v[6:7], v[6:7], v[166:167] op_sel_hi:[1,0]
	v_pk_mul_f32 v[4:5], v[4:5], v[166:167] op_sel_hi:[1,0]
	v_pk_mul_f32 v[2:3], v[2:3], v[166:167] op_sel_hi:[1,0]
	v_pk_mul_f32 v[12:13], v[12:13], v[166:167] op_sel_hi:[1,0]
	v_pk_mul_f32 v[10:11], v[10:11], v[166:167] op_sel_hi:[1,0]
	v_pk_mul_f32 v[16:17], v[16:17], v[166:167] op_sel_hi:[1,0]
	v_pk_mul_f32 v[14:15], v[14:15], v[166:167] op_sel_hi:[1,0]
	v_cvt_pk_bf16_f32 v166, v167, v189
	v_cvt_pk_bf16_f32 v167, v169, v195
	v_cvt_pk_bf16_f32 v168, v175, v197
	v_cvt_pk_bf16_f32 v169, v177, v199
	ds_read2_b64 v[174:177], v95 offset0:128 offset1:132
	v_pk_mul_f32 v[28:29], v[28:29], v[186:187] op_sel_hi:[1,0]
	v_pk_mul_f32 v[26:27], v[26:27], v[186:187] op_sel_hi:[1,0]
	v_pk_add_f32 v[170:171], v[198:199], v[170:171]
	s_waitcnt lgkmcnt(0)
	v_mfma_f32_16x16x32_bf16 v[6:9], v[174:177], v[166:169], v[6:9]
	v_add_f32_e64 v170, v182, v170
	v_add_f32_e64 v171, v183, v171
	v_cvt_pk_bf16_f32 v162, v182, v200
	v_pk_add_f32 v[170:171], v[200:201], v[170:171]
	v_mfma_f32_16x16x32_bf16 v[26:29], v[174:177], v[158:161], v[26:29]
	ds_read2_b64 v[174:177], v95 offset0:136 offset1:140
	v_pk_add_f32 v[170:171], v[184:185], v[170:171]
	v_cvt_pk_bf16_f32 v163, v184, v202
	v_pk_add_f32 v[170:171], v[202:203], v[170:171]
	v_cvt_pk_bf16_f32 v164, v190, v204
	v_pk_add_f32 v[170:171], v[190:191], v[170:171]
	v_cvt_pk_bf16_f32 v165, v192, v206
	v_pk_add_f32 v[170:171], v[204:205], v[170:171]
	v_cvt_pk_bf16_f32 v172, v191, v205
	v_pk_add_f32 v[170:171], v[192:193], v[170:171]
	v_cvt_pk_bf16_f32 v173, v193, v207
	v_pk_add_f32 v[170:171], v[206:207], v[170:171]
	v_add_u32_e32 v95, 0x2800, v93
	v_pk_fma_f32 v[112:113], v[112:113], v[186:187], v[170:171]
	v_cvt_pk_bf16_f32 v170, v183, v201
	v_cvt_pk_bf16_f32 v171, v185, v203
	s_waitcnt lgkmcnt(0)
	v_mfma_f32_16x16x32_bf16 v[26:29], v[174:177], v[162:165], v[26:29]
	v_mul_f32_e64 v20, v20, v186
	v_mul_f32_e64 v21, v21, v186
	v_pk_mul_f32 v[18:19], v[18:19], v[186:187] op_sel_hi:[1,0]
	v_pk_mul_f32 v[24:25], v[24:25], v[186:187] op_sel_hi:[1,0]
	v_mfma_f32_16x16x32_bf16 v[6:9], v[174:177], v[170:173], v[6:9]
	ds_read2_b64 v[174:177], v95 offset0:160 offset1:164
	v_pk_mul_f32 v[22:23], v[22:23], v[186:187] op_sel_hi:[1,0]
	v_pk_mul_f32 v[32:33], v[32:33], v[186:187] op_sel_hi:[1,0]
	s_waitcnt lgkmcnt(0)
	v_mfma_f32_16x16x32_bf16 v[18:21], v[174:177], v[158:161], v[18:21]
	v_mul_f32_e64 v30, v30, v186
	v_mul_f32_e64 v31, v31, v186
	v_mfma_f32_16x16x32_bf16 v[2:5], v[174:177], v[166:169], v[2:5]
	ds_read2_b64 v[174:177], v95 offset0:168 offset1:172
	v_add_u32_e32 v95, 0x3000, v93
	v_add_u32_e32 v93, 0x3800, v93
	s_waitcnt lgkmcnt(0)
	v_mfma_f32_16x16x32_bf16 v[18:21], v[174:177], v[162:165], v[18:21]
	v_mfma_f32_16x16x32_bf16 v[2:5], v[174:177], v[170:173], v[2:5]
	ds_read2_b64 v[174:177], v95 offset0:192 offset1:196
	s_waitcnt lgkmcnt(0)
	v_mfma_f32_16x16x32_bf16 v[22:25], v[174:177], v[158:161], v[22:25]
	v_mfma_f32_16x16x32_bf16 v[10:13], v[174:177], v[166:169], v[10:13]
	ds_read2_b64 v[174:177], v95 offset0:200 offset1:204
	v_mov_b32_e32 v95, v66
	s_waitcnt lgkmcnt(0)
	v_mfma_f32_16x16x32_bf16 v[22:25], v[174:177], v[162:165], v[22:25]
	v_mfma_f32_16x16x32_bf16 v[10:13], v[174:177], v[170:173], v[10:13]
	ds_read2_b64 v[174:177], v93 offset0:224 offset1:228
	s_waitcnt lgkmcnt(0)
	v_mfma_f32_16x16x32_bf16 v[30:33], v[174:177], v[158:161], v[30:33]
	ds_read2_b64 v[158:161], v93 offset0:232 offset1:236
	v_mov_b32_e32 v93, v91
	s_waitcnt lgkmcnt(0)
	v_mfma_f32_16x16x32_bf16 v[14:17], v[174:177], v[166:169], v[14:17]
	s_barrier
	v_mfma_f32_16x16x32_bf16 v[30:33], v[158:161], v[162:165], v[30:33]
	v_mfma_f32_16x16x32_bf16 v[14:17], v[158:161], v[170:173], v[14:17]
	s_cbranch_scc1 .LBB0_1088
	ds_bpermute_b32 v37, v89, v112
	s_lshl_b32 s96, s10, 1
	v_or_b32_e32 v36, v114, v141
	v_lshl_add_u64 v[34:35], v[84:85], 0, s[96:97]
	s_waitcnt lgkmcnt(0)
	v_add_f32_e32 v37, v112, v37
	ds_bpermute_b32 v38, v87, v37
	s_waitcnt lgkmcnt(0)
	v_add_f32_e32 v37, v37, v38
	v_div_scale_f32 v38, s[10:11], v37, v37, 1.0
	v_rcp_f32_e32 v39, v38
	s_nop 0
	v_fma_f32 v40, -v38, v39, 1.0
	v_fmac_f32_e32 v39, v40, v39
	v_div_scale_f32 v40, vcc, 1.0, v37, 1.0
	v_mul_f32_e32 v41, v40, v39
	v_fma_f32 v42, -v38, v41, v40
	v_fmac_f32_e32 v41, v42, v39
	v_fma_f32 v38, -v38, v41, v40
	v_div_fmas_f32 v38, v38, v39, v41
	v_div_fixup_f32 v38, v38, v37, 1.0
	v_ashrrev_i32_e32 v37, 31, v36
	v_lshlrev_b64 v[40:41], 11, v[36:37]
	v_pk_mul_f32 v[18:19], v[18:19], v[38:39] op_sel_hi:[1,0]
	v_pk_mul_f32 v[20:21], v[20:21], v[38:39] op_sel_hi:[1,0]
	v_lshl_add_u64 v[40:41], v[34:35], 0, v[40:41]
	v_cvt_pk_bf16_f32 v18, v18, v19
	v_cvt_pk_bf16_f32 v19, v20, v21
	global_store_dwordx2 v[40:41], v[18:19], off offset:32
	v_pk_mul_f32 v[18:19], v[22:23], v[38:39] op_sel_hi:[1,0]
	v_pk_mul_f32 v[20:21], v[24:25], v[38:39] op_sel_hi:[1,0]
	v_cvt_pk_bf16_f32 v18, v18, v19
	v_cvt_pk_bf16_f32 v19, v20, v21
	global_store_dwordx2 v[40:41], v[18:19], off offset:64
	v_pk_mul_f32 v[18:19], v[30:31], v[38:39] op_sel_hi:[1,0]
	v_pk_mul_f32 v[20:21], v[32:33], v[38:39] op_sel_hi:[1,0]
	v_cvt_pk_bf16_f32 v18, v18, v19
	v_cvt_pk_bf16_f32 v19, v20, v21
	global_store_dwordx2 v[40:41], v[18:19], off offset:96
	ds_bpermute_b32 v18, v89, v113
	v_pk_mul_f32 v[26:27], v[26:27], v[38:39] op_sel_hi:[1,0]
	v_pk_mul_f32 v[28:29], v[28:29], v[38:39] op_sel_hi:[1,0]
	v_cvt_pk_bf16_f32 v26, v26, v27
	v_cvt_pk_bf16_f32 v27, v28, v29
	s_waitcnt lgkmcnt(0)
	v_add_f32_e32 v18, v113, v18
	ds_bpermute_b32 v19, v87, v18
	global_store_dwordx2 v[40:41], v[26:27], off
	s_waitcnt lgkmcnt(0)
	v_add_f32_e32 v18, v18, v19
	v_div_scale_f32 v19, s[10:11], v18, v18, 1.0
	v_rcp_f32_e32 v20, v19
	s_nop 0
	v_fma_f32 v21, -v19, v20, 1.0
	v_fmac_f32_e32 v20, v21, v20
	v_div_scale_f32 v21, vcc, 1.0, v18, 1.0
	v_mul_f32_e32 v22, v21, v20
	v_fma_f32 v23, -v19, v22, v21
	v_fmac_f32_e32 v22, v23, v20
	v_fma_f32 v19, -v19, v22, v21
	v_div_fmas_f32 v19, v19, v20, v22
	v_or_b32_e32 v20, 16, v36
	v_div_fixup_f32 v18, v19, v18, 1.0
	v_ashrrev_i32_e32 v21, 31, v20
	v_lshlrev_b64 v[20:21], 11, v[20:21]
	v_pk_mul_f32 v[2:3], v[2:3], v[18:19] op_sel_hi:[1,0]
	v_pk_mul_f32 v[4:5], v[4:5], v[18:19] op_sel_hi:[1,0]
	v_lshl_add_u64 v[20:21], v[34:35], 0, v[20:21]
	v_cvt_pk_bf16_f32 v2, v2, v3
	v_cvt_pk_bf16_f32 v3, v4, v5
	global_store_dwordx2 v[20:21], v[2:3], off offset:32
	v_pk_mul_f32 v[2:3], v[10:11], v[18:19] op_sel_hi:[1,0]
	v_pk_mul_f32 v[4:5], v[12:13], v[18:19] op_sel_hi:[1,0]
	v_cvt_pk_bf16_f32 v2, v2, v3
	v_cvt_pk_bf16_f32 v3, v4, v5
	v_pk_mul_f32 v[6:7], v[6:7], v[18:19] op_sel_hi:[1,0]
	v_pk_mul_f32 v[8:9], v[8:9], v[18:19] op_sel_hi:[1,0]
	global_store_dwordx2 v[20:21], v[2:3], off offset:64
	v_pk_mul_f32 v[2:3], v[14:15], v[18:19] op_sel_hi:[1,0]
	v_pk_mul_f32 v[4:5], v[16:17], v[18:19] op_sel_hi:[1,0]
	v_cvt_pk_bf16_f32 v6, v6, v7
	v_cvt_pk_bf16_f32 v7, v8, v9
	v_cvt_pk_bf16_f32 v2, v2, v3
	v_cvt_pk_bf16_f32 v3, v4, v5
	global_store_dwordx2 v[20:21], v[6:7], off
	global_store_dwordx2 v[20:21], v[2:3], off offset:96
	s_branch .LBB0_1053
